# same as previous plus extra wait states between the last MFMAs and the SWIGLU epilogue's first accumulator read
# speedup vs baseline: 1.0542x; 1.0098x over previous
; DI float silu_f(float x) { return x * __builtin_amdgcn_rcpf(1.f + __expf(-x)); }
; template <int EPI, int MI>
; DI void gemm_tile(const GemmDesc& g, int tm, int tn, char* smem) {
;     ...
;   if (EPI == EPI_SWIGLU) {
;     u16* es = (u16*)smem;
; #pragma unroll
;     for (int mi = 0; mi < MI; ++mi)
; #pragma unroll
;       for (int i = 0; i < 16; ++i) {
;         const int lrow = wm * (32 * MI) + mi * 32 + (i & 3) + 8 * (i >> 2) + 4 * hh;
;         es[lrow * 64 + wn * 32 + r] = f2bf(silu_f(acc[mi][0][i]) * acc[mi][1][i]);
.LBB0_201:
	s_nop 7
	v_mul_f32_e32 v162, 0xbfb8aa3b, v80
	v_mul_f32_e32 v163, 0xbfb8aa3b, v81
	v_mul_f32_e32 v164, 0xbfb8aa3b, v82
	v_mul_f32_e32 v165, 0xbfb8aa3b, v83
	v_mul_f32_e32 v166, 0xbfb8aa3b, v84
	v_mul_f32_e32 v167, 0xbfb8aa3b, v85
	v_mul_f32_e32 v168, 0xbfb8aa3b, v86
	v_mul_f32_e32 v169, 0xbfb8aa3b, v87
	v_mul_f32_e32 v170, 0xbfb8aa3b, v88
	v_mul_f32_e32 v171, 0xbfb8aa3b, v89
	v_mul_f32_e32 v172, 0xbfb8aa3b, v90
	v_mul_f32_e32 v173, 0xbfb8aa3b, v91
	v_mul_f32_e32 v174, 0xbfb8aa3b, v92
	v_mul_f32_e32 v175, 0xbfb8aa3b, v93
	v_mul_f32_e32 v176, 0xbfb8aa3b, v94
	v_mul_f32_e32 v177, 0xbfb8aa3b, v95
	v_exp_f32_e32 v162, v162
	v_exp_f32_e32 v163, v163
	v_exp_f32_e32 v164, v164
	v_exp_f32_e32 v165, v165
	v_exp_f32_e32 v166, v166
	v_exp_f32_e32 v167, v167
	v_exp_f32_e32 v168, v168
	v_exp_f32_e32 v169, v169
	v_exp_f32_e32 v170, v170
	v_exp_f32_e32 v171, v171
	v_exp_f32_e32 v172, v172
	v_exp_f32_e32 v173, v173
	v_exp_f32_e32 v174, v174
	v_exp_f32_e32 v175, v175
	v_exp_f32_e32 v176, v176
	v_exp_f32_e32 v177, v177
	v_add_f32_e32 v162, 1.0, v162
	v_add_f32_e32 v163, 1.0, v163
	v_add_f32_e32 v164, 1.0, v164
	v_add_f32_e32 v165, 1.0, v165
	v_add_f32_e32 v166, 1.0, v166
	v_add_f32_e32 v167, 1.0, v167
	v_add_f32_e32 v168, 1.0, v168
	v_add_f32_e32 v169, 1.0, v169
	v_add_f32_e32 v170, 1.0, v170
	v_add_f32_e32 v171, 1.0, v171
	v_add_f32_e32 v172, 1.0, v172
	v_add_f32_e32 v173, 1.0, v173
	v_add_f32_e32 v174, 1.0, v174
	v_add_f32_e32 v175, 1.0, v175
	v_add_f32_e32 v176, 1.0, v176
	v_add_f32_e32 v177, 1.0, v177
	v_rcp_f32_e32 v162, v162
	v_rcp_f32_e32 v163, v163
	v_rcp_f32_e32 v164, v164
	v_rcp_f32_e32 v165, v165
	v_rcp_f32_e32 v166, v166
	v_rcp_f32_e32 v167, v167
	v_rcp_f32_e32 v168, v168
	v_rcp_f32_e32 v169, v169
	v_rcp_f32_e32 v170, v170
	v_rcp_f32_e32 v171, v171
	v_rcp_f32_e32 v172, v172
	v_rcp_f32_e32 v173, v173
	v_rcp_f32_e32 v174, v174
	v_rcp_f32_e32 v175, v175
	v_rcp_f32_e32 v176, v176
	v_rcp_f32_e32 v177, v177
	v_mul_f32_e32 v80, v80, v162
	v_mul_f32_e32 v81, v81, v163
	v_mul_f32_e32 v82, v82, v164
	v_mul_f32_e32 v83, v83, v165
	v_mul_f32_e32 v84, v84, v166
	v_mul_f32_e32 v85, v85, v167
	v_mul_f32_e32 v86, v86, v168
	v_mul_f32_e32 v87, v87, v169
	v_mul_f32_e32 v88, v88, v170
	v_mul_f32_e32 v89, v89, v171
	v_mul_f32_e32 v90, v90, v172
	v_mul_f32_e32 v91, v91, v173
	v_mul_f32_e32 v92, v92, v174
	v_mul_f32_e32 v93, v93, v175
	v_mul_f32_e32 v94, v94, v176
	v_mul_f32_e32 v95, v95, v177
	v_mul_f32_e32 v80, v64, v80
	v_mul_f32_e32 v81, v65, v81
	v_mul_f32_e32 v82, v66, v82
	v_mul_f32_e32 v83, v67, v83
	v_mul_f32_e32 v84, v68, v84
	v_mul_f32_e32 v85, v69, v85
	v_mul_f32_e32 v86, v70, v86
	v_mul_f32_e32 v87, v71, v87
	v_mul_f32_e32 v88, v72, v88
	v_mul_f32_e32 v89, v73, v89
	v_mul_f32_e32 v90, v74, v90
	v_mul_f32_e32 v91, v75, v91
	v_mul_f32_e32 v92, v76, v92
	v_mul_f32_e32 v93, v77, v93
	v_mul_f32_e32 v94, v78, v94
	v_mul_f32_e32 v95, v79, v95
	v_cvt_pk_bf16_f32 v80, v80, s0
	v_cvt_pk_bf16_f32 v81, v81, s0
	v_cvt_pk_bf16_f32 v82, v82, s0
	v_cvt_pk_bf16_f32 v83, v83, s0
	v_cvt_pk_bf16_f32 v84, v84, s0
	v_cvt_pk_bf16_f32 v85, v85, s0
	v_cvt_pk_bf16_f32 v86, v86, s0
	v_cvt_pk_bf16_f32 v87, v87, s0
	v_cvt_pk_bf16_f32 v88, v88, s0
	v_cvt_pk_bf16_f32 v89, v89, s0
	v_cvt_pk_bf16_f32 v90, v90, s0
	v_cvt_pk_bf16_f32 v91, v91, s0
	v_cvt_pk_bf16_f32 v92, v92, s0
	v_cvt_pk_bf16_f32 v93, v93, s0
	v_cvt_pk_bf16_f32 v94, v94, s0
	v_cvt_pk_bf16_f32 v95, v95, s0
	v_mul_f32_e32 v162, 0xbfb8aa3b, v48
	v_mul_f32_e32 v163, 0xbfb8aa3b, v49
	v_mul_f32_e32 v164, 0xbfb8aa3b, v50
	v_mul_f32_e32 v165, 0xbfb8aa3b, v51
	v_mul_f32_e32 v166, 0xbfb8aa3b, v52
	v_mul_f32_e32 v167, 0xbfb8aa3b, v53
	v_mul_f32_e32 v168, 0xbfb8aa3b, v54
	v_mul_f32_e32 v169, 0xbfb8aa3b, v55
	v_mul_f32_e32 v170, 0xbfb8aa3b, v56
	v_mul_f32_e32 v171, 0xbfb8aa3b, v57
	v_mul_f32_e32 v172, 0xbfb8aa3b, v58
	v_mul_f32_e32 v173, 0xbfb8aa3b, v59
	v_mul_f32_e32 v174, 0xbfb8aa3b, v60
	v_mul_f32_e32 v175, 0xbfb8aa3b, v61
	v_mul_f32_e32 v176, 0xbfb8aa3b, v62
	v_mul_f32_e32 v177, 0xbfb8aa3b, v63
	v_exp_f32_e32 v162, v162
	v_exp_f32_e32 v163, v163
	v_exp_f32_e32 v164, v164
	v_exp_f32_e32 v165, v165
	v_exp_f32_e32 v166, v166
	v_exp_f32_e32 v167, v167
	v_exp_f32_e32 v168, v168
	v_exp_f32_e32 v169, v169
	v_exp_f32_e32 v170, v170
	v_exp_f32_e32 v171, v171
	v_exp_f32_e32 v172, v172
	v_exp_f32_e32 v173, v173
	v_exp_f32_e32 v174, v174
	v_exp_f32_e32 v175, v175
	v_exp_f32_e32 v176, v176
	v_exp_f32_e32 v177, v177
	v_add_f32_e32 v162, 1.0, v162
	v_add_f32_e32 v163, 1.0, v163
	v_add_f32_e32 v164, 1.0, v164
	v_add_f32_e32 v165, 1.0, v165
	v_add_f32_e32 v166, 1.0, v166
	v_add_f32_e32 v167, 1.0, v167
	v_add_f32_e32 v168, 1.0, v168
	v_add_f32_e32 v169, 1.0, v169
	v_add_f32_e32 v170, 1.0, v170
	v_add_f32_e32 v171, 1.0, v171
	v_add_f32_e32 v172, 1.0, v172
	v_add_f32_e32 v173, 1.0, v173
	v_add_f32_e32 v174, 1.0, v174
	v_add_f32_e32 v175, 1.0, v175
	v_add_f32_e32 v176, 1.0, v176
	v_add_f32_e32 v177, 1.0, v177
	v_rcp_f32_e32 v162, v162
	v_rcp_f32_e32 v163, v163
	v_rcp_f32_e32 v164, v164
	v_rcp_f32_e32 v165, v165
	v_rcp_f32_e32 v166, v166
	v_rcp_f32_e32 v167, v167
	v_rcp_f32_e32 v168, v168
	v_rcp_f32_e32 v169, v169
	v_rcp_f32_e32 v170, v170
	v_rcp_f32_e32 v171, v171
	v_rcp_f32_e32 v172, v172
	v_rcp_f32_e32 v173, v173
	v_rcp_f32_e32 v174, v174
	v_rcp_f32_e32 v175, v175
	v_rcp_f32_e32 v176, v176
	v_rcp_f32_e32 v177, v177
	v_mul_f32_e32 v48, v48, v162
	v_mul_f32_e32 v49, v49, v163
	v_mul_f32_e32 v50, v50, v164
	v_mul_f32_e32 v51, v51, v165
	v_mul_f32_e32 v52, v52, v166
	v_mul_f32_e32 v53, v53, v167
	v_mul_f32_e32 v54, v54, v168
	v_mul_f32_e32 v55, v55, v169
	v_mul_f32_e32 v56, v56, v170
	v_mul_f32_e32 v57, v57, v171
	v_mul_f32_e32 v58, v58, v172
; DI float silu_f(float x) { return x * __builtin_amdgcn_rcpf(1.f + __expf(-x)); }
; template <int EPI, int MI>
; DI void gemm_tile(const GemmDesc& g, int tm, int tn, char* smem) {
;     ...
;   if (EPI == EPI_SWIGLU) {
;     u16* es = (u16*)smem;
; #pragma unroll
;     for (int mi = 0; mi < MI; ++mi)
; #pragma unroll
;       for (int i = 0; i < 16; ++i) {
;         const int lrow = wm * (32 * MI) + mi * 32 + (i & 3) + 8 * (i >> 2) + 4 * hh;
;         es[lrow * 64 + wn * 32 + r] = f2bf(silu_f(acc[mi][0][i]) * acc[mi][1][i]);
;       }
;     __syncthreads();
	v_mul_f32_e32 v59, v59, v173
	v_mul_f32_e32 v60, v60, v174
	v_mul_f32_e32 v61, v61, v175
	v_mul_f32_e32 v62, v62, v176
	v_mul_f32_e32 v63, v63, v177
	v_mul_f32_e32 v48, v32, v48
	v_mul_f32_e32 v49, v33, v49
	v_mul_f32_e32 v50, v34, v50
	v_mul_f32_e32 v51, v35, v51
	v_mul_f32_e32 v52, v36, v52
	v_mul_f32_e32 v53, v37, v53
	v_mul_f32_e32 v54, v38, v54
	v_mul_f32_e32 v55, v39, v55
	v_mul_f32_e32 v56, v40, v56
	v_mul_f32_e32 v57, v41, v57
	v_mul_f32_e32 v58, v42, v58
	v_mul_f32_e32 v59, v43, v59
	v_mul_f32_e32 v60, v44, v60
	v_mul_f32_e32 v61, v45, v61
	v_mul_f32_e32 v62, v46, v62
	v_mul_f32_e32 v63, v47, v63
	v_cvt_pk_bf16_f32 v48, v48, s0
	v_cvt_pk_bf16_f32 v49, v49, s0
	v_cvt_pk_bf16_f32 v50, v50, s0
	v_cvt_pk_bf16_f32 v51, v51, s0
	v_cvt_pk_bf16_f32 v52, v52, s0
	v_cvt_pk_bf16_f32 v53, v53, s0
	v_cvt_pk_bf16_f32 v54, v54, s0
	v_cvt_pk_bf16_f32 v55, v55, s0
	v_cvt_pk_bf16_f32 v56, v56, s0
	v_cvt_pk_bf16_f32 v57, v57, s0
	v_cvt_pk_bf16_f32 v58, v58, s0
	v_cvt_pk_bf16_f32 v59, v59, s0
	v_cvt_pk_bf16_f32 v60, v60, s0
	v_cvt_pk_bf16_f32 v61, v61, s0
	v_cvt_pk_bf16_f32 v62, v62, s0
	v_cvt_pk_bf16_f32 v63, v63, s0
	v_mul_f32_e32 v162, 0xbfb8aa3b, v16
	v_mul_f32_e32 v163, 0xbfb8aa3b, v17
	v_mul_f32_e32 v164, 0xbfb8aa3b, v18
	v_mul_f32_e32 v165, 0xbfb8aa3b, v19
	v_mul_f32_e32 v166, 0xbfb8aa3b, v20
	v_mul_f32_e32 v167, 0xbfb8aa3b, v21
	v_mul_f32_e32 v168, 0xbfb8aa3b, v22
	v_mul_f32_e32 v169, 0xbfb8aa3b, v23
	v_mul_f32_e32 v170, 0xbfb8aa3b, v24
	v_mul_f32_e32 v171, 0xbfb8aa3b, v25
	v_mul_f32_e32 v172, 0xbfb8aa3b, v26
	v_mul_f32_e32 v173, 0xbfb8aa3b, v27
	v_mul_f32_e32 v174, 0xbfb8aa3b, v28
	v_mul_f32_e32 v175, 0xbfb8aa3b, v29
	v_mul_f32_e32 v176, 0xbfb8aa3b, v30
	v_mul_f32_e32 v177, 0xbfb8aa3b, v31
	v_exp_f32_e32 v162, v162
	v_exp_f32_e32 v163, v163
	v_exp_f32_e32 v164, v164
	v_exp_f32_e32 v165, v165
	v_exp_f32_e32 v166, v166
	v_exp_f32_e32 v167, v167
	v_exp_f32_e32 v168, v168
	v_exp_f32_e32 v169, v169
	v_exp_f32_e32 v170, v170
	v_exp_f32_e32 v171, v171
	v_exp_f32_e32 v172, v172
	v_exp_f32_e32 v173, v173
	v_exp_f32_e32 v174, v174
	v_exp_f32_e32 v175, v175
	v_exp_f32_e32 v176, v176
	v_exp_f32_e32 v177, v177
	v_add_f32_e32 v162, 1.0, v162
	v_add_f32_e32 v163, 1.0, v163
	v_add_f32_e32 v164, 1.0, v164
	v_add_f32_e32 v165, 1.0, v165
	v_add_f32_e32 v166, 1.0, v166
	v_add_f32_e32 v167, 1.0, v167
	v_add_f32_e32 v168, 1.0, v168
	v_add_f32_e32 v169, 1.0, v169
	v_add_f32_e32 v170, 1.0, v170
	v_add_f32_e32 v171, 1.0, v171
	v_add_f32_e32 v172, 1.0, v172
	v_add_f32_e32 v173, 1.0, v173
	v_add_f32_e32 v174, 1.0, v174
	v_add_f32_e32 v175, 1.0, v175
	v_add_f32_e32 v176, 1.0, v176
	v_add_f32_e32 v177, 1.0, v177
	v_rcp_f32_e32 v162, v162
	v_rcp_f32_e32 v163, v163
	v_rcp_f32_e32 v164, v164
	v_rcp_f32_e32 v165, v165
	v_rcp_f32_e32 v166, v166
	v_rcp_f32_e32 v167, v167
	v_rcp_f32_e32 v168, v168
	v_rcp_f32_e32 v169, v169
	v_rcp_f32_e32 v170, v170
	v_rcp_f32_e32 v171, v171
	v_rcp_f32_e32 v172, v172
	v_rcp_f32_e32 v173, v173
	v_rcp_f32_e32 v174, v174
	v_rcp_f32_e32 v175, v175
	v_rcp_f32_e32 v176, v176
	v_rcp_f32_e32 v177, v177
	v_mul_f32_e32 v16, v16, v162
	v_mul_f32_e32 v17, v17, v163
	v_mul_f32_e32 v18, v18, v164
	v_mul_f32_e32 v19, v19, v165
	v_mul_f32_e32 v20, v20, v166
	v_mul_f32_e32 v21, v21, v167
	v_mul_f32_e32 v22, v22, v168
	v_mul_f32_e32 v23, v23, v169
	v_mul_f32_e32 v24, v24, v170
	v_mul_f32_e32 v25, v25, v171
	v_mul_f32_e32 v26, v26, v172
	v_mul_f32_e32 v27, v27, v173
	v_mul_f32_e32 v28, v28, v174
	v_mul_f32_e32 v29, v29, v175
	v_mul_f32_e32 v30, v30, v176
	v_mul_f32_e32 v31, v31, v177
	v_mul_f32_e32 v16, v0, v16
	v_mul_f32_e32 v17, v1, v17
	v_mul_f32_e32 v18, v2, v18
	v_mul_f32_e32 v19, v3, v19
	v_mul_f32_e32 v20, v4, v20
	v_mul_f32_e32 v21, v5, v21
	v_mul_f32_e32 v22, v6, v22
	v_mul_f32_e32 v23, v7, v23
	v_mul_f32_e32 v24, v8, v24
	v_mul_f32_e32 v25, v9, v25
	v_mul_f32_e32 v26, v10, v26
	v_mul_f32_e32 v27, v11, v27
	v_mul_f32_e32 v28, v12, v28
	v_mul_f32_e32 v29, v13, v29
	v_mul_f32_e32 v30, v14, v30
	v_mul_f32_e32 v31, v15, v31
	v_cvt_pk_bf16_f32 v16, v16, s0
	v_cvt_pk_bf16_f32 v17, v17, s0
	v_cvt_pk_bf16_f32 v18, v18, s0
	v_cvt_pk_bf16_f32 v19, v19, s0
	v_cvt_pk_bf16_f32 v20, v20, s0
	v_cvt_pk_bf16_f32 v21, v21, s0
	v_cvt_pk_bf16_f32 v22, v22, s0
	v_cvt_pk_bf16_f32 v23, v23, s0
	v_cvt_pk_bf16_f32 v24, v24, s0
	v_cvt_pk_bf16_f32 v25, v25, s0
	v_cvt_pk_bf16_f32 v26, v26, s0
	v_cvt_pk_bf16_f32 v27, v27, s0
	v_cvt_pk_bf16_f32 v28, v28, s0
	v_cvt_pk_bf16_f32 v29, v29, s0
	v_cvt_pk_bf16_f32 v30, v30, s0
	v_cvt_pk_bf16_f32 v31, v31, s0
	v_lshlrev_b32_e32 v99, 9, v122
	v_lshlrev_b32_e32 v100, 6, v123
	v_add3_u32 v99, 0, v99, v100
	v_lshlrev_b32_e32 v100, 1, v121
	v_readlane_b32 s16, v221, 5
	v_readlane_b32 s17, v221, 6
	s_movk_i32 s0, 0x3000
	v_mul_lo_u32 v64, v120, s0
	v_add3_u32 v64, v99, v100, v64
	s_movk_i32 s15, 0x1600
	v_lshlrev_b32_e32 v4, 4, v115
	v_mov_b32_e32 v5, v96
	v_mov_b64_e32 v[6:7], s[16:17]
	v_mad_i64_i32 v[8:9], s[16:17], v98, s15, v[6:7]
	v_add_u32_e32 v10, 0, v4
	v_lshl_add_u32 v0, v97, 7, v10
	ds_write_b16 v64, v80
	ds_write_b16 v64, v81 offset:128
	ds_write_b16 v64, v82 offset:256
	ds_write_b16 v64, v83 offset:384
	ds_write_b16 v64, v84 offset:1024
	ds_write_b16 v64, v85 offset:1152
	ds_write_b16 v64, v86 offset:1280
	ds_write_b16 v64, v87 offset:1408
	ds_write_b16 v64, v88 offset:2048
	ds_write_b16 v64, v89 offset:2176
	ds_write_b16 v64, v90 offset:2304
	ds_write_b16 v64, v91 offset:2432
	ds_write_b16 v64, v92 offset:3072
	ds_write_b16 v64, v93 offset:3200
	ds_write_b16 v64, v94 offset:3328
	ds_write_b16 v64, v95 offset:3456
	ds_write_b16 v64, v48 offset:4096
	ds_write_b16 v64, v49 offset:4224
	ds_write_b16 v64, v50 offset:4352
	ds_write_b16 v64, v51 offset:4480
	ds_write_b16 v64, v52 offset:5120
	ds_write_b16 v64, v53 offset:5248
	ds_write_b16 v64, v54 offset:5376
	ds_write_b16 v64, v55 offset:5504
	ds_write_b16 v64, v56 offset:6144
	ds_write_b16 v64, v57 offset:6272
	ds_write_b16 v64, v58 offset:6400
	ds_write_b16 v64, v59 offset:6528
	ds_write_b16 v64, v60 offset:7168
	ds_write_b16 v64, v61 offset:7296
	ds_write_b16 v64, v62 offset:7424
	ds_write_b16 v64, v63 offset:7552
	ds_write_b16 v64, v16 offset:8192
	ds_write_b16 v64, v17 offset:8320
	ds_write_b16 v64, v18 offset:8448
	ds_write_b16 v64, v19 offset:8576
	ds_write_b16 v64, v20 offset:9216
	ds_write_b16 v64, v21 offset:9344
	ds_write_b16 v64, v22 offset:9472
	ds_write_b16 v64, v23 offset:9600
	ds_write_b16 v64, v24 offset:10240
	ds_write_b16 v64, v25 offset:10368
	ds_write_b16 v64, v26 offset:10496
	ds_write_b16 v64, v27 offset:10624
	ds_write_b16 v64, v28 offset:11264
	ds_write_b16 v64, v29 offset:11392
	ds_write_b16 v64, v30 offset:11520
	ds_write_b16 v64, v31 offset:11648
	s_waitcnt lgkmcnt(0)
	s_barrier
; template <int EPI, int MI>
; DI void gemm_tile(const GemmDesc& g, int tm, int tn, char* smem) {
;     ...
; #pragma unroll
;     for (int j = 0; j < 2 * MI; ++j) {
;       const int lrow = (tid >> 3) + 32 * j, ch = tid & 7;
;       const u32x4 v = *(const u32x4*)(es + lrow * 64 + ch * 8);
;       *(u32x4*)(g.o16 + (size_t)(m0 + lrow) * g.ldo + (n0 >> 1) + ch * 8) = v;
;     }
;     __syncthreads();
; template <int EPI, int MI>
; DI void gemm_phase(const GemmDesc& g, char* smem, int vb, int nvb) {
;     ...
;   for (int q = start; q < local; q += step) {
;     const int mg = q / per;
;     const int rem = q - mg * per;
;     const int tn = rem / PM;
;     const int tm = mbase + mg * PM + (rem - tn * PM);
;     gemm_tile<EPI, MI>(g, tm, tn, smem);
	s_lshl_b32 s0, s39, 6
	ds_read_b128 v[0:3], v0
	s_ashr_i32 s1, s0, 31
	s_lshl_b64 s[0:1], s[0:1], 1
	v_lshl_add_u64 v[8:9], v[8:9], 0, s[0:1]
	v_lshl_add_u64 v[8:9], v[8:9], 0, v[4:5]
	s_waitcnt lgkmcnt(0)
	global_store_dwordx4 v[8:9], v[0:3], off
	v_add_u32_e32 v8, 32, v97
	s_nop 0
	v_lshl_add_u32 v0, v8, 7, v10
	ds_read_b128 v[0:3], v0
	v_add_u32_e32 v8, s38, v8
	v_mad_i64_i32 v[8:9], s[16:17], v8, s15, v[6:7]
	v_lshl_add_u64 v[8:9], v[8:9], 0, s[0:1]
	v_lshl_add_u64 v[8:9], v[8:9], 0, v[4:5]
	s_waitcnt lgkmcnt(0)
	global_store_dwordx4 v[8:9], v[0:3], off
	v_add_u32_e32 v8, 64, v97
	s_nop 0
	v_lshl_add_u32 v0, v8, 7, v10
	ds_read_b128 v[0:3], v0
	v_add_u32_e32 v8, s38, v8
	v_mad_i64_i32 v[8:9], s[16:17], v8, s15, v[6:7]
	v_lshl_add_u64 v[8:9], v[8:9], 0, s[0:1]
	v_lshl_add_u64 v[8:9], v[8:9], 0, v[4:5]
	s_waitcnt lgkmcnt(0)
	global_store_dwordx4 v[8:9], v[0:3], off
	v_add_u32_e32 v8, 0x60, v97
	s_nop 0
	v_lshl_add_u32 v0, v8, 7, v10
	ds_read_b128 v[0:3], v0
	v_add_u32_e32 v8, s38, v8
	v_mad_i64_i32 v[8:9], s[16:17], v8, s15, v[6:7]
	v_lshl_add_u64 v[8:9], v[8:9], 0, s[0:1]
	v_lshl_add_u64 v[8:9], v[8:9], 0, v[4:5]
	s_waitcnt lgkmcnt(0)
	global_store_dwordx4 v[8:9], v[0:3], off
	v_add_u32_e32 v8, 0x80, v97
	s_nop 0
	v_lshl_add_u32 v0, v8, 7, v10
	ds_read_b128 v[0:3], v0
	v_add_u32_e32 v8, s38, v8
	v_mad_i64_i32 v[8:9], s[16:17], v8, s15, v[6:7]
	v_lshl_add_u64 v[8:9], v[8:9], 0, s[0:1]
	v_lshl_add_u64 v[8:9], v[8:9], 0, v[4:5]
	s_waitcnt lgkmcnt(0)
	global_store_dwordx4 v[8:9], v[0:3], off
	v_add_u32_e32 v8, 0xa0, v97
	s_nop 0
	v_lshl_add_u32 v0, v8, 7, v10
	v_add_u32_e32 v8, s38, v8
	ds_read_b128 v[0:3], v0
	v_mad_i64_i32 v[6:7], s[16:17], v8, s15, v[6:7]
	v_lshl_add_u64 v[6:7], v[6:7], 0, s[0:1]
	v_readlane_b32 s0, v218, 38
	s_add_i32 s5, s5, s0
	v_readlane_b32 s0, v218, 31
	s_add_i32 s4, s4, s0
	v_readlane_b32 s0, v221, 7
	v_lshl_add_u64 v[4:5], v[6:7], 0, v[4:5]
	s_cmp_lt_i32 s5, s0
	s_waitcnt lgkmcnt(0)
	global_store_dwordx4 v[4:5], v[0:3], off
	s_barrier
	s_cbranch_scc0 .LBB0_198

; DI float silu_f(float x) { return x * __builtin_amdgcn_rcpf(1.f + __expf(-x)); }
; template <int EPI, int MI>
; DI void gemm_tile(const GemmDesc& g, int tm, int tn, char* smem) {
;     ...
;   if (EPI == EPI_SWIGLU) {
;     u16* es = (u16*)smem;
; #pragma unroll
;     for (int mi = 0; mi < MI; ++mi)
; #pragma unroll
;       for (int i = 0; i < 16; ++i) {
;         const int lrow = wm * (32 * MI) + mi * 32 + (i & 3) + 8 * (i >> 2) + 4 * hh;
;         es[lrow * 64 + wn * 32 + r] = f2bf(silu_f(acc[mi][0][i]) * acc[mi][1][i]);
.LBB0_1420:
	s_nop 7
	v_mul_f32_e32 v162, 0xbfb8aa3b, v80
	v_mul_f32_e32 v163, 0xbfb8aa3b, v81
	v_mul_f32_e32 v164, 0xbfb8aa3b, v82
	v_mul_f32_e32 v165, 0xbfb8aa3b, v83
	v_mul_f32_e32 v166, 0xbfb8aa3b, v84
	v_mul_f32_e32 v167, 0xbfb8aa3b, v85
	v_mul_f32_e32 v168, 0xbfb8aa3b, v86
	v_mul_f32_e32 v169, 0xbfb8aa3b, v87
	v_mul_f32_e32 v170, 0xbfb8aa3b, v88
	v_mul_f32_e32 v171, 0xbfb8aa3b, v89
	v_mul_f32_e32 v172, 0xbfb8aa3b, v90
	v_mul_f32_e32 v173, 0xbfb8aa3b, v91
	v_mul_f32_e32 v174, 0xbfb8aa3b, v92
	v_mul_f32_e32 v175, 0xbfb8aa3b, v93
	v_mul_f32_e32 v176, 0xbfb8aa3b, v94
	v_mul_f32_e32 v177, 0xbfb8aa3b, v95
	v_exp_f32_e32 v162, v162
	v_exp_f32_e32 v163, v163
	v_exp_f32_e32 v164, v164
	v_exp_f32_e32 v165, v165
	v_exp_f32_e32 v166, v166
	v_exp_f32_e32 v167, v167
	v_exp_f32_e32 v168, v168
	v_exp_f32_e32 v169, v169
	v_exp_f32_e32 v170, v170
	v_exp_f32_e32 v171, v171
	v_exp_f32_e32 v172, v172
	v_exp_f32_e32 v173, v173
	v_exp_f32_e32 v174, v174
	v_exp_f32_e32 v175, v175
	v_exp_f32_e32 v176, v176
	v_exp_f32_e32 v177, v177
	v_add_f32_e32 v162, 1.0, v162
	v_add_f32_e32 v163, 1.0, v163
	v_add_f32_e32 v164, 1.0, v164
	v_add_f32_e32 v165, 1.0, v165
	v_add_f32_e32 v166, 1.0, v166
	v_add_f32_e32 v167, 1.0, v167
	v_add_f32_e32 v168, 1.0, v168
	v_add_f32_e32 v169, 1.0, v169
	v_add_f32_e32 v170, 1.0, v170
	v_add_f32_e32 v171, 1.0, v171
	v_add_f32_e32 v172, 1.0, v172
	v_add_f32_e32 v173, 1.0, v173
	v_add_f32_e32 v174, 1.0, v174
	v_add_f32_e32 v175, 1.0, v175
	v_add_f32_e32 v176, 1.0, v176
	v_add_f32_e32 v177, 1.0, v177
	v_rcp_f32_e32 v162, v162
	v_rcp_f32_e32 v163, v163
	v_rcp_f32_e32 v164, v164
	v_rcp_f32_e32 v165, v165
	v_rcp_f32_e32 v166, v166
	v_rcp_f32_e32 v167, v167
	v_rcp_f32_e32 v168, v168
	v_rcp_f32_e32 v169, v169
	v_rcp_f32_e32 v170, v170
	v_rcp_f32_e32 v171, v171
	v_rcp_f32_e32 v172, v172
	v_rcp_f32_e32 v173, v173
	v_rcp_f32_e32 v174, v174
	v_rcp_f32_e32 v175, v175
	v_rcp_f32_e32 v176, v176
	v_rcp_f32_e32 v177, v177
	v_mul_f32_e32 v80, v80, v162
	v_mul_f32_e32 v81, v81, v163
	v_mul_f32_e32 v82, v82, v164
	v_mul_f32_e32 v83, v83, v165
	v_mul_f32_e32 v84, v84, v166
	v_mul_f32_e32 v85, v85, v167
	v_mul_f32_e32 v86, v86, v168
	v_mul_f32_e32 v87, v87, v169
	v_mul_f32_e32 v88, v88, v170
	v_mul_f32_e32 v89, v89, v171
	v_mul_f32_e32 v90, v90, v172
	v_mul_f32_e32 v91, v91, v173
	v_mul_f32_e32 v92, v92, v174
	v_mul_f32_e32 v93, v93, v175
	v_mul_f32_e32 v94, v94, v176
	v_mul_f32_e32 v95, v95, v177
	v_mul_f32_e32 v80, v64, v80
	v_mul_f32_e32 v81, v65, v81
	v_mul_f32_e32 v82, v66, v82
	v_mul_f32_e32 v83, v67, v83
	v_mul_f32_e32 v84, v68, v84
	v_mul_f32_e32 v85, v69, v85
	v_mul_f32_e32 v86, v70, v86
	v_mul_f32_e32 v87, v71, v87
	v_mul_f32_e32 v88, v72, v88
	v_mul_f32_e32 v89, v73, v89
	v_mul_f32_e32 v90, v74, v90
	v_mul_f32_e32 v91, v75, v91
	v_mul_f32_e32 v92, v76, v92
	v_mul_f32_e32 v93, v77, v93
	v_mul_f32_e32 v94, v78, v94
	v_mul_f32_e32 v95, v79, v95
	v_cvt_pk_bf16_f32 v80, v80, s0
	v_cvt_pk_bf16_f32 v81, v81, s0
	v_cvt_pk_bf16_f32 v82, v82, s0
	v_cvt_pk_bf16_f32 v83, v83, s0
	v_cvt_pk_bf16_f32 v84, v84, s0
	v_cvt_pk_bf16_f32 v85, v85, s0
	v_cvt_pk_bf16_f32 v86, v86, s0
	v_cvt_pk_bf16_f32 v87, v87, s0
	v_cvt_pk_bf16_f32 v88, v88, s0
	v_cvt_pk_bf16_f32 v89, v89, s0
	v_cvt_pk_bf16_f32 v90, v90, s0
	v_cvt_pk_bf16_f32 v91, v91, s0
	v_cvt_pk_bf16_f32 v92, v92, s0
	v_cvt_pk_bf16_f32 v93, v93, s0
	v_cvt_pk_bf16_f32 v94, v94, s0
	v_cvt_pk_bf16_f32 v95, v95, s0
	v_mul_f32_e32 v162, 0xbfb8aa3b, v48
	v_mul_f32_e32 v163, 0xbfb8aa3b, v49
	v_mul_f32_e32 v164, 0xbfb8aa3b, v50
	v_mul_f32_e32 v165, 0xbfb8aa3b, v51
	v_mul_f32_e32 v166, 0xbfb8aa3b, v52
	v_mul_f32_e32 v167, 0xbfb8aa3b, v53
	v_mul_f32_e32 v168, 0xbfb8aa3b, v54
	v_mul_f32_e32 v169, 0xbfb8aa3b, v55
	v_mul_f32_e32 v170, 0xbfb8aa3b, v56
	v_mul_f32_e32 v171, 0xbfb8aa3b, v57
	v_mul_f32_e32 v172, 0xbfb8aa3b, v58
	v_mul_f32_e32 v173, 0xbfb8aa3b, v59
	v_mul_f32_e32 v174, 0xbfb8aa3b, v60
	v_mul_f32_e32 v175, 0xbfb8aa3b, v61
	v_mul_f32_e32 v176, 0xbfb8aa3b, v62
	v_mul_f32_e32 v177, 0xbfb8aa3b, v63
	v_exp_f32_e32 v162, v162
	v_exp_f32_e32 v163, v163
	v_exp_f32_e32 v164, v164
	v_exp_f32_e32 v165, v165
	v_exp_f32_e32 v166, v166
	v_exp_f32_e32 v167, v167
	v_exp_f32_e32 v168, v168
	v_exp_f32_e32 v169, v169
	v_exp_f32_e32 v170, v170
	v_exp_f32_e32 v171, v171
	v_exp_f32_e32 v172, v172
	v_exp_f32_e32 v173, v173
	v_exp_f32_e32 v174, v174
	v_exp_f32_e32 v175, v175
	v_exp_f32_e32 v176, v176
	v_exp_f32_e32 v177, v177
	v_add_f32_e32 v162, 1.0, v162
	v_add_f32_e32 v163, 1.0, v163
	v_add_f32_e32 v164, 1.0, v164
	v_add_f32_e32 v165, 1.0, v165
	v_add_f32_e32 v166, 1.0, v166
	v_add_f32_e32 v167, 1.0, v167
	v_add_f32_e32 v168, 1.0, v168
	v_add_f32_e32 v169, 1.0, v169
	v_add_f32_e32 v170, 1.0, v170
	v_add_f32_e32 v171, 1.0, v171
	v_add_f32_e32 v172, 1.0, v172
	v_add_f32_e32 v173, 1.0, v173
	v_add_f32_e32 v174, 1.0, v174
	v_add_f32_e32 v175, 1.0, v175
	v_add_f32_e32 v176, 1.0, v176
	v_add_f32_e32 v177, 1.0, v177
	v_rcp_f32_e32 v162, v162
	v_rcp_f32_e32 v163, v163
	v_rcp_f32_e32 v164, v164
	v_rcp_f32_e32 v165, v165
	v_rcp_f32_e32 v166, v166
	v_rcp_f32_e32 v167, v167
	v_rcp_f32_e32 v168, v168
	v_rcp_f32_e32 v169, v169
	v_rcp_f32_e32 v170, v170
	v_rcp_f32_e32 v171, v171
	v_rcp_f32_e32 v172, v172
	v_rcp_f32_e32 v173, v173
	v_rcp_f32_e32 v174, v174
	v_rcp_f32_e32 v175, v175
	v_rcp_f32_e32 v176, v176
	v_rcp_f32_e32 v177, v177
	v_mul_f32_e32 v48, v48, v162
	v_mul_f32_e32 v49, v49, v163
	v_mul_f32_e32 v50, v50, v164
	v_mul_f32_e32 v51, v51, v165
	v_mul_f32_e32 v52, v52, v166
	v_mul_f32_e32 v53, v53, v167
	v_mul_f32_e32 v54, v54, v168
	v_mul_f32_e32 v55, v55, v169
	v_mul_f32_e32 v56, v56, v170
	v_mul_f32_e32 v57, v57, v171
	v_mul_f32_e32 v58, v58, v172
; DI float silu_f(float x) { return x * __builtin_amdgcn_rcpf(1.f + __expf(-x)); }
; template <int EPI, int MI>
; DI void gemm_tile(const GemmDesc& g, int tm, int tn, char* smem) {
;     ...
;   if (EPI == EPI_SWIGLU) {
;     u16* es = (u16*)smem;
; #pragma unroll
;     for (int mi = 0; mi < MI; ++mi)
; #pragma unroll
;       for (int i = 0; i < 16; ++i) {
;         const int lrow = wm * (32 * MI) + mi * 32 + (i & 3) + 8 * (i >> 2) + 4 * hh;
;         es[lrow * 64 + wn * 32 + r] = f2bf(silu_f(acc[mi][0][i]) * acc[mi][1][i]);
;       }
;     __syncthreads();
	v_mul_f32_e32 v59, v59, v173
	v_mul_f32_e32 v60, v60, v174
	v_mul_f32_e32 v61, v61, v175
	v_mul_f32_e32 v62, v62, v176
	v_mul_f32_e32 v63, v63, v177
	v_mul_f32_e32 v48, v32, v48
	v_mul_f32_e32 v49, v33, v49
	v_mul_f32_e32 v50, v34, v50
	v_mul_f32_e32 v51, v35, v51
	v_mul_f32_e32 v52, v36, v52
	v_mul_f32_e32 v53, v37, v53
	v_mul_f32_e32 v54, v38, v54
	v_mul_f32_e32 v55, v39, v55
	v_mul_f32_e32 v56, v40, v56
	v_mul_f32_e32 v57, v41, v57
	v_mul_f32_e32 v58, v42, v58
	v_mul_f32_e32 v59, v43, v59
	v_mul_f32_e32 v60, v44, v60
	v_mul_f32_e32 v61, v45, v61
	v_mul_f32_e32 v62, v46, v62
	v_mul_f32_e32 v63, v47, v63
	v_cvt_pk_bf16_f32 v48, v48, s0
	v_cvt_pk_bf16_f32 v49, v49, s0
	v_cvt_pk_bf16_f32 v50, v50, s0
	v_cvt_pk_bf16_f32 v51, v51, s0
	v_cvt_pk_bf16_f32 v52, v52, s0
	v_cvt_pk_bf16_f32 v53, v53, s0
	v_cvt_pk_bf16_f32 v54, v54, s0
	v_cvt_pk_bf16_f32 v55, v55, s0
	v_cvt_pk_bf16_f32 v56, v56, s0
	v_cvt_pk_bf16_f32 v57, v57, s0
	v_cvt_pk_bf16_f32 v58, v58, s0
	v_cvt_pk_bf16_f32 v59, v59, s0
	v_cvt_pk_bf16_f32 v60, v60, s0
	v_cvt_pk_bf16_f32 v61, v61, s0
	v_cvt_pk_bf16_f32 v62, v62, s0
	v_cvt_pk_bf16_f32 v63, v63, s0
	v_mul_f32_e32 v162, 0xbfb8aa3b, v16
	v_mul_f32_e32 v163, 0xbfb8aa3b, v17
	v_mul_f32_e32 v164, 0xbfb8aa3b, v18
	v_mul_f32_e32 v165, 0xbfb8aa3b, v19
	v_mul_f32_e32 v166, 0xbfb8aa3b, v20
	v_mul_f32_e32 v167, 0xbfb8aa3b, v21
	v_mul_f32_e32 v168, 0xbfb8aa3b, v22
	v_mul_f32_e32 v169, 0xbfb8aa3b, v23
	v_mul_f32_e32 v170, 0xbfb8aa3b, v24
	v_mul_f32_e32 v171, 0xbfb8aa3b, v25
	v_mul_f32_e32 v172, 0xbfb8aa3b, v26
	v_mul_f32_e32 v173, 0xbfb8aa3b, v27
	v_mul_f32_e32 v174, 0xbfb8aa3b, v28
	v_mul_f32_e32 v175, 0xbfb8aa3b, v29
	v_mul_f32_e32 v176, 0xbfb8aa3b, v30
	v_mul_f32_e32 v177, 0xbfb8aa3b, v31
	v_exp_f32_e32 v162, v162
	v_exp_f32_e32 v163, v163
	v_exp_f32_e32 v164, v164
	v_exp_f32_e32 v165, v165
	v_exp_f32_e32 v166, v166
	v_exp_f32_e32 v167, v167
	v_exp_f32_e32 v168, v168
	v_exp_f32_e32 v169, v169
	v_exp_f32_e32 v170, v170
	v_exp_f32_e32 v171, v171
	v_exp_f32_e32 v172, v172
	v_exp_f32_e32 v173, v173
	v_exp_f32_e32 v174, v174
	v_exp_f32_e32 v175, v175
	v_exp_f32_e32 v176, v176
	v_exp_f32_e32 v177, v177
	v_add_f32_e32 v162, 1.0, v162
	v_add_f32_e32 v163, 1.0, v163
	v_add_f32_e32 v164, 1.0, v164
	v_add_f32_e32 v165, 1.0, v165
	v_add_f32_e32 v166, 1.0, v166
	v_add_f32_e32 v167, 1.0, v167
	v_add_f32_e32 v168, 1.0, v168
	v_add_f32_e32 v169, 1.0, v169
	v_add_f32_e32 v170, 1.0, v170
	v_add_f32_e32 v171, 1.0, v171
	v_add_f32_e32 v172, 1.0, v172
	v_add_f32_e32 v173, 1.0, v173
	v_add_f32_e32 v174, 1.0, v174
	v_add_f32_e32 v175, 1.0, v175
	v_add_f32_e32 v176, 1.0, v176
	v_add_f32_e32 v177, 1.0, v177
	v_rcp_f32_e32 v162, v162
	v_rcp_f32_e32 v163, v163
	v_rcp_f32_e32 v164, v164
	v_rcp_f32_e32 v165, v165
	v_rcp_f32_e32 v166, v166
	v_rcp_f32_e32 v167, v167
	v_rcp_f32_e32 v168, v168
	v_rcp_f32_e32 v169, v169
	v_rcp_f32_e32 v170, v170
	v_rcp_f32_e32 v171, v171
	v_rcp_f32_e32 v172, v172
	v_rcp_f32_e32 v173, v173
	v_rcp_f32_e32 v174, v174
	v_rcp_f32_e32 v175, v175
	v_rcp_f32_e32 v176, v176
	v_rcp_f32_e32 v177, v177
	v_mul_f32_e32 v16, v16, v162
	v_mul_f32_e32 v17, v17, v163
	v_mul_f32_e32 v18, v18, v164
	v_mul_f32_e32 v19, v19, v165
	v_mul_f32_e32 v20, v20, v166
	v_mul_f32_e32 v21, v21, v167
	v_mul_f32_e32 v22, v22, v168
	v_mul_f32_e32 v23, v23, v169
	v_mul_f32_e32 v24, v24, v170
	v_mul_f32_e32 v25, v25, v171
	v_mul_f32_e32 v26, v26, v172
	v_mul_f32_e32 v27, v27, v173
	v_mul_f32_e32 v28, v28, v174
	v_mul_f32_e32 v29, v29, v175
	v_mul_f32_e32 v30, v30, v176
	v_mul_f32_e32 v31, v31, v177
	v_mul_f32_e32 v16, v0, v16
	v_mul_f32_e32 v17, v1, v17
	v_mul_f32_e32 v18, v2, v18
	v_mul_f32_e32 v19, v3, v19
	v_mul_f32_e32 v20, v4, v20
	v_mul_f32_e32 v21, v5, v21
	v_mul_f32_e32 v22, v6, v22
	v_mul_f32_e32 v23, v7, v23
	v_mul_f32_e32 v24, v8, v24
	v_mul_f32_e32 v25, v9, v25
	v_mul_f32_e32 v26, v10, v26
	v_mul_f32_e32 v27, v11, v27
	v_mul_f32_e32 v28, v12, v28
	v_mul_f32_e32 v29, v13, v29
	v_mul_f32_e32 v30, v14, v30
	v_mul_f32_e32 v31, v15, v31
	v_cvt_pk_bf16_f32 v16, v16, s0
	v_cvt_pk_bf16_f32 v17, v17, s0
	v_cvt_pk_bf16_f32 v18, v18, s0
	v_cvt_pk_bf16_f32 v19, v19, s0
	v_cvt_pk_bf16_f32 v20, v20, s0
	v_cvt_pk_bf16_f32 v21, v21, s0
	v_cvt_pk_bf16_f32 v22, v22, s0
	v_cvt_pk_bf16_f32 v23, v23, s0
	v_cvt_pk_bf16_f32 v24, v24, s0
	v_cvt_pk_bf16_f32 v25, v25, s0
	v_cvt_pk_bf16_f32 v26, v26, s0
	v_cvt_pk_bf16_f32 v27, v27, s0
	v_cvt_pk_bf16_f32 v28, v28, s0
	v_cvt_pk_bf16_f32 v29, v29, s0
	v_cvt_pk_bf16_f32 v30, v30, s0
	v_cvt_pk_bf16_f32 v31, v31, s0
	v_lshlrev_b32_e32 v99, 9, v122
	v_lshlrev_b32_e32 v100, 6, v123
	v_add3_u32 v99, 0, v99, v100
	v_lshlrev_b32_e32 v100, 1, v121
	v_readlane_b32 s16, v221, 5
	v_readlane_b32 s17, v221, 6
	s_movk_i32 s0, 0x3000
	v_mul_lo_u32 v64, v120, s0
	v_add3_u32 v64, v99, v100, v64
	s_movk_i32 s15, 0x1600
	v_lshlrev_b32_e32 v4, 4, v115
	v_mov_b32_e32 v5, v96
	v_mov_b64_e32 v[6:7], s[16:17]
	v_mad_i64_i32 v[8:9], s[16:17], v98, s15, v[6:7]
	v_add_u32_e32 v10, 0, v4
	v_lshl_add_u32 v0, v97, 7, v10
	ds_write_b16 v64, v80
	ds_write_b16 v64, v81 offset:128
	ds_write_b16 v64, v82 offset:256
	ds_write_b16 v64, v83 offset:384
	ds_write_b16 v64, v84 offset:1024
	ds_write_b16 v64, v85 offset:1152
	ds_write_b16 v64, v86 offset:1280
	ds_write_b16 v64, v87 offset:1408
	ds_write_b16 v64, v88 offset:2048
	ds_write_b16 v64, v89 offset:2176
	ds_write_b16 v64, v90 offset:2304
	ds_write_b16 v64, v91 offset:2432
	ds_write_b16 v64, v92 offset:3072
	ds_write_b16 v64, v93 offset:3200
	ds_write_b16 v64, v94 offset:3328
	ds_write_b16 v64, v95 offset:3456
	ds_write_b16 v64, v48 offset:4096
	ds_write_b16 v64, v49 offset:4224
	ds_write_b16 v64, v50 offset:4352
	ds_write_b16 v64, v51 offset:4480
	ds_write_b16 v64, v52 offset:5120
	ds_write_b16 v64, v53 offset:5248
	ds_write_b16 v64, v54 offset:5376
	ds_write_b16 v64, v55 offset:5504
	ds_write_b16 v64, v56 offset:6144
	ds_write_b16 v64, v57 offset:6272
	ds_write_b16 v64, v58 offset:6400
	ds_write_b16 v64, v59 offset:6528
	ds_write_b16 v64, v60 offset:7168
	ds_write_b16 v64, v61 offset:7296
	ds_write_b16 v64, v62 offset:7424
	ds_write_b16 v64, v63 offset:7552
	ds_write_b16 v64, v16 offset:8192
	ds_write_b16 v64, v17 offset:8320
	ds_write_b16 v64, v18 offset:8448
	ds_write_b16 v64, v19 offset:8576
	ds_write_b16 v64, v20 offset:9216
	ds_write_b16 v64, v21 offset:9344
	ds_write_b16 v64, v22 offset:9472
	ds_write_b16 v64, v23 offset:9600
	ds_write_b16 v64, v24 offset:10240
	ds_write_b16 v64, v25 offset:10368
	ds_write_b16 v64, v26 offset:10496
	ds_write_b16 v64, v27 offset:10624
	ds_write_b16 v64, v28 offset:11264
	ds_write_b16 v64, v29 offset:11392
	ds_write_b16 v64, v30 offset:11520
	ds_write_b16 v64, v31 offset:11648
	s_waitcnt lgkmcnt(0)
	s_barrier
; template <int EPI, int MI>
; DI void gemm_tile(const GemmDesc& g, int tm, int tn, char* smem) {
;     ...
; #pragma unroll
;     for (int j = 0; j < 2 * MI; ++j) {
;       const int lrow = (tid >> 3) + 32 * j, ch = tid & 7;
;       const u32x4 v = *(const u32x4*)(es + lrow * 64 + ch * 8);
;       *(u32x4*)(g.o16 + (size_t)(m0 + lrow) * g.ldo + (n0 >> 1) + ch * 8) = v;
;     }
;     __syncthreads();
; template <int EPI, int MI>
; DI void gemm_phase(const GemmDesc& g, char* smem, int vb, int nvb) {
;     ...
;   for (int q = start; q < local; q += step) {
;     const int mg = q / per;
;     const int rem = q - mg * per;
;     const int tn = rem / PM;
;     const int tm = mbase + mg * PM + (rem - tn * PM);
;     gemm_tile<EPI, MI>(g, tm, tn, smem);
	s_lshl_b32 s0, s39, 6
	ds_read_b128 v[0:3], v0
	s_ashr_i32 s1, s0, 31
	s_lshl_b64 s[0:1], s[0:1], 1
	v_lshl_add_u64 v[8:9], v[8:9], 0, s[0:1]
	v_lshl_add_u64 v[8:9], v[8:9], 0, v[4:5]
	s_waitcnt lgkmcnt(0)
	global_store_dwordx4 v[8:9], v[0:3], off
	v_add_u32_e32 v8, 32, v97
	s_nop 0
	v_lshl_add_u32 v0, v8, 7, v10
	ds_read_b128 v[0:3], v0
	v_add_u32_e32 v8, s38, v8
	v_mad_i64_i32 v[8:9], s[16:17], v8, s15, v[6:7]
	v_lshl_add_u64 v[8:9], v[8:9], 0, s[0:1]
	v_lshl_add_u64 v[8:9], v[8:9], 0, v[4:5]
	s_waitcnt lgkmcnt(0)
	global_store_dwordx4 v[8:9], v[0:3], off
	v_add_u32_e32 v8, 64, v97
	s_nop 0
	v_lshl_add_u32 v0, v8, 7, v10
	ds_read_b128 v[0:3], v0
	v_add_u32_e32 v8, s38, v8
	v_mad_i64_i32 v[8:9], s[16:17], v8, s15, v[6:7]
	v_lshl_add_u64 v[8:9], v[8:9], 0, s[0:1]
	v_lshl_add_u64 v[8:9], v[8:9], 0, v[4:5]
	s_waitcnt lgkmcnt(0)
	global_store_dwordx4 v[8:9], v[0:3], off
	v_add_u32_e32 v8, 0x60, v97
	s_nop 0
	v_lshl_add_u32 v0, v8, 7, v10
	ds_read_b128 v[0:3], v0
	v_add_u32_e32 v8, s38, v8
	v_mad_i64_i32 v[8:9], s[16:17], v8, s15, v[6:7]
	v_lshl_add_u64 v[8:9], v[8:9], 0, s[0:1]
	v_lshl_add_u64 v[8:9], v[8:9], 0, v[4:5]
	s_waitcnt lgkmcnt(0)
	global_store_dwordx4 v[8:9], v[0:3], off
	v_add_u32_e32 v8, 0x80, v97
	s_nop 0
	v_lshl_add_u32 v0, v8, 7, v10
	ds_read_b128 v[0:3], v0
	v_add_u32_e32 v8, s38, v8
	v_mad_i64_i32 v[8:9], s[16:17], v8, s15, v[6:7]
	v_lshl_add_u64 v[8:9], v[8:9], 0, s[0:1]
	v_lshl_add_u64 v[8:9], v[8:9], 0, v[4:5]
	s_waitcnt lgkmcnt(0)
	global_store_dwordx4 v[8:9], v[0:3], off
	v_add_u32_e32 v8, 0xa0, v97
	s_nop 0
	v_lshl_add_u32 v0, v8, 7, v10
	v_add_u32_e32 v8, s38, v8
	ds_read_b128 v[0:3], v0
	v_mad_i64_i32 v[6:7], s[16:17], v8, s15, v[6:7]
	v_lshl_add_u64 v[6:7], v[6:7], 0, s[0:1]
	v_readlane_b32 s0, v218, 38
	s_add_i32 s5, s5, s0
	v_readlane_b32 s0, v218, 31
	s_add_i32 s4, s4, s0
	v_readlane_b32 s0, v221, 7
	v_lshl_add_u64 v[4:5], v[6:7], 0, v[4:5]
	s_cmp_ge_i32 s5, s0
	s_waitcnt lgkmcnt(0)
	global_store_dwordx4 v[4:5], v[0:3], off
	s_barrier
	s_cbranch_scc1 .LBB0_1417
